# first-barrier counter loads issued back-to-back (were 16 serialized round trips)
# speedup vs baseline: 1.0044x; 1.0044x over previous
; DI unsigned xb_ld(unsigned* p) { return __hip_atomic_load(p, __ATOMIC_RELAXED, __HIP_MEMORY_SCOPE_AGENT); }
; DI void xcd_barrier_complete(unsigned* bar, unsigned x, unsigned& nloc, unsigned& nx) {
;     ...
;   for (;;) {
;     sum = 0u; cnt = 0u; mine = 0u;
; #pragma unroll
;     for (unsigned j = 0; j < 16; ++j) { const unsigned c = xb_ld(&bar[XB_XCNT(j)]); sum += c; cnt += (c > 0u) ? 1u : 0u; mine = (j == x) ? c : mine; }
;     if (sum == G) break;
;     __builtin_amdgcn_s_sleep(1);
;     if ((++sp & 255u) == 0u) { if (xb_ld(&bar[XB_TMO])) break; if (sp > XB_SPIN_CAP) { atomicAdd(&bar[XB_TMO], 1u); break; } }
.LBB0_115:
	v_readlane_b32 s4, v253, 12
	s_waitcnt lgkmcnt(0)
	v_readlane_b32 s2, v253, 32
	v_readlane_b32 s3, v253, 33
	s_nop 4
	global_load_dword v0, v17, s[2:3] sc1
	v_readlane_b32 s2, v253, 34
	v_readlane_b32 s3, v253, 35
	s_nop 4
	global_load_dword v1, v17, s[2:3] sc1
	v_readlane_b32 s2, v253, 36
	v_readlane_b32 s3, v253, 37
	s_nop 4
	global_load_dword v2, v17, s[2:3] sc1
	v_readlane_b32 s2, v253, 38
	v_readlane_b32 s3, v253, 39
	s_nop 4
	global_load_dword v3, v17, s[2:3] sc1
	v_readlane_b32 s2, v253, 40
	v_readlane_b32 s3, v253, 41
	s_nop 4
	global_load_dword v5, v17, s[2:3] sc1
	v_readlane_b32 s2, v253, 42
	v_readlane_b32 s3, v253, 43
	s_nop 4
	global_load_dword v6, v17, s[2:3] sc1
	v_readlane_b32 s2, v253, 44
	v_readlane_b32 s3, v253, 45
	s_nop 4
	global_load_dword v7, v17, s[2:3] sc1
	v_readlane_b32 s2, v253, 46
	v_readlane_b32 s3, v253, 47
	s_nop 4
	global_load_dword v8, v17, s[2:3] sc1
	v_readlane_b32 s2, v253, 48
	v_readlane_b32 s3, v253, 49
	s_nop 4
	global_load_dword v9, v17, s[2:3] sc1
	v_readlane_b32 s2, v253, 50
	v_readlane_b32 s3, v253, 51
	s_nop 4
	global_load_dword v10, v17, s[2:3] sc1
	v_readlane_b32 s2, v253, 52
	v_readlane_b32 s3, v253, 53
	s_nop 4
	global_load_dword v11, v17, s[2:3] sc1
	v_readlane_b32 s2, v253, 54
	v_readlane_b32 s3, v253, 55
	s_nop 4
	global_load_dword v12, v17, s[2:3] sc1
	v_readlane_b32 s2, v253, 56
	v_readlane_b32 s3, v253, 57
	s_nop 4
	global_load_dword v13, v17, s[2:3] sc1
	v_readlane_b32 s2, v253, 58
	v_readlane_b32 s3, v253, 59
	s_nop 4
	global_load_dword v14, v17, s[2:3] sc1
	v_readlane_b32 s2, v253, 60
	v_readlane_b32 s3, v253, 61
	s_nop 4
	global_load_dword v15, v17, s[2:3] sc1
	v_readlane_b32 s2, v253, 62
	v_readlane_b32 s3, v253, 63
	s_nop 4
	global_load_dword v16, v17, s[2:3] sc1
	s_mov_b64 s[2:3], -1
	s_waitcnt vmcnt(0)
	v_add_u32_e32 v18, v1, v0
	v_add_u32_e32 v18, v18, v2
	v_add_u32_e32 v18, v18, v3
	v_add_u32_e32 v18, v18, v5
	v_add_u32_e32 v18, v18, v6
	v_add_u32_e32 v18, v18, v7
	v_add_u32_e32 v18, v18, v8
	v_add_u32_e32 v18, v18, v9
	v_add_u32_e32 v18, v18, v10
	v_add_u32_e32 v18, v18, v11
	v_add_u32_e32 v18, v18, v12
	v_add_u32_e32 v18, v18, v13
	v_add_u32_e32 v18, v18, v14
	v_add_u32_e32 v18, v18, v15
	v_add_u32_e32 v18, v18, v16
	v_cmp_eq_u32_e32 vcc, s4, v18
	s_mov_b64 s[4:5], -1
	s_cbranch_vccnz .LBB0_114
	s_and_b32 s2, s8, 0xff
	s_cmp_eq_u32 s2, 0
	s_mov_b64 s[2:3], -1
	s_mov_b64 s[6:7], -1
	s_sleep 1
	s_cbranch_scc1 .LBB0_119
	s_and_b64 vcc, exec, s[6:7]
	s_cbranch_vccz .LBB0_114
